# work queue: next ticket atomic issued just before each unit's final stores (late prefetch), consumed at the loop top
# speedup vs baseline: 1.0020x; 1.0020x over previous
.LBB0_1513:
	s_or_b64 exec, exec, s[0:1]
	v_readlane_b32 s0, v254, 28
	s_waitcnt lgkmcnt(0)
	s_barrier
	s_lshl_b32 s94, s12, 7
	v_mov_b32_e32 v0, s0
	ds_read2_b32 v[2:3], v0 offset1:1
	s_lshl_b64 s[0:1], s[94:95], 2
	s_movk_i32 s25, 0x2000
	s_waitcnt lgkmcnt(0)
	v_readfirstlane_b32 s2, v2
	v_readfirstlane_b32 s3, v3
	s_add_u32 s2, s2, s0
	s_addc_u32 s3, s3, s1
	s_nop 2
	global_load_dwordx4 v[2:5], v1, s[2:3] offset:48
	global_load_dwordx4 v[6:9], v1, s[2:3] offset:32
	global_load_dwordx4 v[10:13], v1, s[2:3] offset:16
	global_load_dwordx4 v[14:17], v1, s[2:3]
	global_load_dwordx4 v[18:21], v1, s[2:3] offset:176
	global_load_dwordx4 v[22:25], v1, s[2:3] offset:160
	global_load_dwordx4 v[26:29], v1, s[2:3] offset:144
	global_load_dwordx4 v[30:33], v1, s[2:3] offset:128
	global_load_dwordx4 v[34:37], v1, s[2:3] offset:304
	global_load_dwordx4 v[38:41], v1, s[2:3] offset:288
	global_load_dwordx4 v[42:45], v1, s[2:3] offset:272
	global_load_dwordx4 v[46:49], v1, s[2:3] offset:256
	global_load_dwordx4 v[50:53], v1, s[2:3] offset:432
	global_load_dwordx4 v[54:57], v1, s[2:3] offset:416
	global_load_dwordx4 v[58:61], v1, s[2:3] offset:400
	global_load_dwordx4 v[62:65], v1, s[2:3] offset:384
	s_add_i32 s48, s12, 1
	s_lshl_b32 s94, s48, 6
	s_waitcnt vmcnt(8)
	v_fma_f32 v0, v14, v30, 0
	v_fmac_f32_e32 v0, v15, v31
	s_waitcnt vmcnt(0)
	v_fma_f32 v14, v46, v62, 0
	v_fmac_f32_e32 v0, v16, v32
	v_fmac_f32_e32 v14, v47, v63
	v_fmac_f32_e32 v0, v17, v33
	v_fmac_f32_e32 v14, v48, v64
	v_fmac_f32_e32 v0, v10, v26
	v_fmac_f32_e32 v14, v49, v65
	v_fmac_f32_e32 v0, v11, v27
	v_fmac_f32_e32 v14, v42, v58
	v_fmac_f32_e32 v0, v12, v28
	v_fmac_f32_e32 v14, v43, v59
	v_fmac_f32_e32 v0, v13, v29
	v_fmac_f32_e32 v14, v44, v60
	v_fmac_f32_e32 v0, v6, v22
	v_fmac_f32_e32 v14, v45, v61
	v_fmac_f32_e32 v0, v7, v23
	v_fmac_f32_e32 v14, v38, v54
	v_fmac_f32_e32 v0, v8, v24
	v_fmac_f32_e32 v14, v39, v55
	v_fmac_f32_e32 v0, v9, v25
	v_fmac_f32_e32 v14, v40, v56
	v_fmac_f32_e32 v0, v2, v18
	v_fmac_f32_e32 v14, v41, v57
	v_fmac_f32_e32 v0, v3, v19
	v_fmac_f32_e32 v14, v34, v50
	v_fmac_f32_e32 v0, v4, v20
	v_fmac_f32_e32 v14, v35, v51
	v_fmac_f32_e32 v0, v5, v21
	global_load_dwordx4 v[2:5], v1, s[2:3] offset:112
	global_load_dwordx4 v[6:9], v1, s[2:3] offset:96
	global_load_dwordx4 v[10:13], v1, s[2:3] offset:80
	global_load_dwordx4 v[16:19], v1, s[2:3] offset:64
	global_load_dwordx4 v[20:23], v1, s[2:3] offset:240
	global_load_dwordx4 v[24:27], v1, s[2:3] offset:224
	global_load_dwordx4 v[28:31], v1, s[2:3] offset:208
	global_load_dwordx4 v[32:35], v1, s[2:3] offset:192
	v_fmac_f32_e32 v14, v36, v52
	v_fmac_f32_e32 v14, v37, v53
	global_load_dwordx4 v[36:39], v1, s[2:3] offset:368
	global_load_dwordx4 v[40:43], v1, s[2:3] offset:352
	global_load_dwordx4 v[44:47], v1, s[2:3] offset:336
	global_load_dwordx4 v[48:51], v1, s[2:3] offset:320
	global_load_dwordx4 v[52:55], v1, s[2:3] offset:496
	global_load_dwordx4 v[56:59], v1, s[2:3] offset:480
	global_load_dwordx4 v[60:63], v1, s[2:3] offset:464
	global_load_dwordx4 v[64:67], v1, s[2:3] offset:448
	s_mov_b32 s2, s33
	s_waitcnt vmcnt(8)
	v_fmac_f32_e32 v0, v16, v32
	v_fmac_f32_e32 v0, v17, v33
	v_fmac_f32_e32 v0, v18, v34
	v_fmac_f32_e32 v0, v19, v35
	v_fmac_f32_e32 v0, v10, v28
	v_fmac_f32_e32 v0, v11, v29
	s_waitcnt vmcnt(0)
	v_fmac_f32_e32 v14, v48, v64
	v_fmac_f32_e32 v0, v12, v30
	v_fmac_f32_e32 v14, v49, v65
	v_fmac_f32_e32 v0, v13, v31
	v_fmac_f32_e32 v14, v50, v66
	v_fmac_f32_e32 v0, v6, v24
	v_fmac_f32_e32 v14, v51, v67
	v_fmac_f32_e32 v0, v7, v25
	v_fmac_f32_e32 v14, v44, v60
	v_fmac_f32_e32 v0, v8, v26
	v_fmac_f32_e32 v14, v45, v61
	v_fmac_f32_e32 v0, v9, v27
	v_fmac_f32_e32 v14, v46, v62
	v_fmac_f32_e32 v0, v2, v20
	v_cvt_f32_u32_e32 v2, s12
	v_fmac_f32_e32 v14, v47, v63
	v_fmac_f32_e32 v14, v40, v56
	v_fmac_f32_e32 v14, v41, v57
	v_fmac_f32_e32 v14, v42, v58
	v_mul_f32_e32 v2, 0xbe99999a, v2
	v_fmac_f32_e32 v14, v43, v59
	v_mul_f32_e32 v2, 0x3fb8aa3b, v2
	v_fmac_f32_e32 v14, v36, v52
	v_exp_f32_e32 v2, v2
	v_fmac_f32_e32 v0, v3, v21
	v_fmac_f32_e32 v14, v37, v53
	v_fmac_f32_e32 v0, v4, v22
	v_fmac_f32_e32 v14, v38, v54
	v_fmac_f32_e32 v0, v5, v23
	v_fmac_f32_e32 v14, v39, v55
	v_mov_b32_e32 v3, 0x3f4ccccd
	v_fmamk_f32 v4, v2, 0xbf19999a, v3
	v_mul_f32_e32 v0, 0x3fb8aa3b, v0
	v_mul_f32_e32 v2, 0x3fb8aa3b, v14
	v_exp_f32_e32 v0, v0
	v_exp_f32_e32 v2, v2
	v_sub_f32_e32 v185, 1.0, v4
	v_sub_f32_e32 v0, v0, v2
	v_add_f32_e32 v175, v4, v0
	v_mov_b32_e32 v0, s2
	ds_read2_b32 v[2:3], v0 offset1:1
	s_lshl_b64 s[2:3], s[94:95], 2
	s_waitcnt lgkmcnt(0)
	v_readfirstlane_b32 s4, v2
	s_add_u32 s30, s4, s2
	s_mov_b32 s2, s33
	v_readfirstlane_b32 s5, v3
	v_mov_b32_e32 v0, s2
	ds_read2_b32 v[2:3], v0 offset1:1
	s_addc_u32 s31, s5, s3
	s_lshl_b32 s87, s12, 1
	s_waitcnt lgkmcnt(0)
	v_readfirstlane_b32 s2, v2
	v_readfirstlane_b32 s3, v3
	s_add_u32 s2, s2, s0
	s_addc_u32 s3, s3, s1
	s_add_u32 s92, s2, 0x400
	s_mov_b32 s2, s33
	s_addc_u32 s93, s3, 0
	v_mov_b32_e32 v0, s2
	ds_read2_b32 v[2:3], v0 offset1:1
	s_waitcnt lgkmcnt(0)
	v_readfirstlane_b32 s2, v2
	v_readfirstlane_b32 s3, v3
	s_add_u32 s0, s2, s0
	s_addc_u32 s1, s3, s1
	s_add_u32 s36, s0, 0x500
	s_addc_u32 s37, s1, 0
	s_lshl_b32 s0, s12, 6
	s_mov_b32 s1, s95
	v_writelane_b32 v254, s0, 57
	s_lshl_b32 s94, s12, 5
	s_nop 0
	v_writelane_b32 v254, s1, 58
	s_lshl_b32 s0, s12, 9
	v_writelane_b32 v254, s0, 59
	s_add_u32 s0, s51, s54
	s_addc_u32 s1, s56, 0
	s_add_u32 s0, s0, 0x3380080
	s_addc_u32 s1, s1, 0
	v_writelane_b32 v254, s0, 61
	s_mov_b32 s54, 0x8000
	s_nop 0
	v_writelane_b32 v254, s1, 62
	s_lshl_b64 s[0:1], s[94:95], 2
	v_writelane_b32 v254, s0, 63
	s_nop 0
	v_readlane_b32 s56, v254, 54
	v_writelane_b32 v255, s1, 0
	s_mov_b32 s32, 0
	s_branch .LBB0_1518

.LBB0_1518:
	v_mov_b32_e32 v0, v1
	s_barrier
	s_getreg_b32 s0, hwreg(HW_REG_HW_ID, 0, 6)
	s_lshl_b32 s0, s0, 2
	s_and_b32 s0, s0, 0xfc
	v_add_u32_e32 v2, s0, v0
	v_add_u32_e32 v2, 0x24800, v2
	ds_read_b32 v2, v2
	v_mbcnt_lo_u32_b32 v0, -1, v0
	v_mbcnt_hi_u32_b32 v0, -1, v0
	s_waitcnt lgkmcnt(0)
	v_readfirstlane_b32 s0, v2
	s_lshl_b32 s0, s0, 6
	s_sub_i32 s0, 0, s0
	v_cmp_eq_u32_e32 vcc, s0, v0
	s_and_saveexec_b64 s[0:1], vcc
	s_cbranch_execz .LBB0_1522
	s_mov_b64 s[4:5], exec
	v_mbcnt_lo_u32_b32 v0, s4, 0
	v_mbcnt_hi_u32_b32 v0, s5, v0
	v_cmp_eq_u32_e32 vcc, 0, v0
	s_and_saveexec_b64 s[2:3], vcc
	s_cbranch_execz .LBB0_1521
	s_cmp_eq_u32 s32, 0
	s_cbranch_scc0 .Lq_have
	s_bcnt1_i32_b64 s4, s[4:5]
	v_mov_b32_e32 v2, s4
	global_atomic_add v2, v1, v2, s[30:31] sc0
	s_mov_b32 s32, 1
	s_branch .LBB0_1521
.Lq_have:
	s_waitcnt vmcnt(0)
	v_mov_b32_e32 v2, v252

.LBB0_1670:
	s_waitcnt lgkmcnt(0)
	v_add_f32_e32 v0, v194, v195
	v_max_f32_e32 v0, 0xda24260, v0
	s_waitcnt vmcnt(0)
	v_div_scale_f32 v2, s[0:1], v0, v0, v173
	v_rcp_f32_e32 v3, v2
	s_barrier
	v_fma_f32 v4, -v2, v3, 1.0
	v_fmac_f32_e32 v3, v4, v3
	v_div_scale_f32 v4, vcc, v173, v0, v173
	v_mul_f32_e32 v5, v4, v3
	v_fma_f32 v6, -v2, v5, v4
	v_fmac_f32_e32 v5, v6, v3
	v_fma_f32 v2, -v2, v5, v4
	v_div_fmas_f32 v2, v2, v3, v5
	v_div_fixup_f32 v0, v2, v0, v173
	v_mov_b32_e32 v2, v1
	v_pk_mul_f32 v[8:9], v[16:17], v[190:191] op_sel_hi:[1,0]
	v_mbcnt_lo_u32_b32 v2, -1, v2
	v_mbcnt_hi_u32_b32 v2, -1, v2
	v_lshlrev_b32_e32 v2, 2, v2
	v_xor_b32_e32 v2, 0x80, v2
	ds_bpermute_b32 v2, v2, v196
	v_pk_mul_f32 v[10:11], v[34:35], v[190:191] op_sel_hi:[1,0]
	v_pk_mul_f32 v[12:13], v[18:19], v[190:191] op_sel_hi:[1,0]
	v_pk_mul_f32 v[14:15], v[36:37], v[190:191] op_sel_hi:[1,0]
	v_pk_mul_f32 v[16:17], v[20:21], v[190:191] op_sel_hi:[1,0]
	s_waitcnt lgkmcnt(0)
	v_add_f32_e32 v2, v196, v2
	v_max_f32_e32 v2, 0xda24260, v2
	v_div_scale_f32 v3, s[0:1], v2, v2, v174
	v_rcp_f32_e32 v4, v3
	v_pk_mul_f32 v[18:19], v[38:39], v[190:191] op_sel_hi:[1,0]
	v_pk_mul_f32 v[20:21], v[22:23], v[190:191] op_sel_hi:[1,0]
	v_pk_mul_f32 v[22:23], v[40:41], v[190:191] op_sel_hi:[1,0]
	v_fma_f32 v5, -v3, v4, 1.0
	v_fmac_f32_e32 v4, v5, v4
	v_div_scale_f32 v5, vcc, v174, v2, v174
	v_mul_f32_e32 v6, v5, v4
	v_fma_f32 v7, -v3, v6, v5
	v_fmac_f32_e32 v6, v7, v4
	v_fma_f32 v3, -v3, v6, v5
	v_div_fmas_f32 v3, v3, v4, v6
	v_pk_mul_f32 v[4:5], v[64:65], v[0:1] op_sel_hi:[1,0]
	v_pk_mul_f32 v[6:7], v[32:33], v[190:191] op_sel_hi:[1,0]
	v_pk_mul_f32 v[24:25], v[24:25], v[190:191] op_sel_hi:[1,0]
	v_pk_fma_f32 v[4:5], v[172:173], v[6:7], v[4:5] op_sel_hi:[0,1,1]
	v_pk_mul_f32 v[6:7], v[48:49], v[0:1] op_sel_hi:[1,0]
	v_pk_mul_f32 v[32:33], v[42:43], v[190:191] op_sel_hi:[1,0]
	v_pk_fma_f32 v[6:7], v[172:173], v[8:9], v[6:7] op_sel_hi:[0,1,1]
	v_pk_mul_f32 v[8:9], v[66:67], v[0:1] op_sel_hi:[1,0]
	v_pk_mul_f32 v[26:27], v[26:27], v[190:191] op_sel_hi:[1,0]
	v_pk_fma_f32 v[8:9], v[172:173], v[10:11], v[8:9] op_sel_hi:[0,1,1]
	v_pk_mul_f32 v[10:11], v[50:51], v[0:1] op_sel_hi:[1,0]
	v_pk_mul_f32 v[34:35], v[44:45], v[190:191] op_sel_hi:[1,0]
	v_pk_fma_f32 v[10:11], v[172:173], v[12:13], v[10:11] op_sel_hi:[0,1,1]
	v_pk_mul_f32 v[12:13], v[68:69], v[0:1] op_sel_hi:[1,0]
	v_pk_mul_f32 v[28:29], v[28:29], v[190:191] op_sel_hi:[1,0]
	v_pk_fma_f32 v[12:13], v[172:173], v[14:15], v[12:13] op_sel_hi:[0,1,1]
	v_pk_mul_f32 v[14:15], v[52:53], v[0:1] op_sel_hi:[1,0]
	v_pk_mul_f32 v[36:37], v[46:47], v[190:191] op_sel_hi:[1,0]
	v_pk_fma_f32 v[14:15], v[172:173], v[16:17], v[14:15] op_sel_hi:[0,1,1]
	v_pk_mul_f32 v[16:17], v[70:71], v[0:1] op_sel_hi:[1,0]
	v_pk_mul_f32 v[30:31], v[30:31], v[190:191] op_sel_hi:[1,0]
	v_pk_fma_f32 v[16:17], v[172:173], v[18:19], v[16:17] op_sel_hi:[0,1,1]
	v_pk_mul_f32 v[18:19], v[54:55], v[0:1] op_sel_hi:[1,0]
	v_div_fixup_f32 v2, v3, v2, v174
	v_pk_fma_f32 v[18:19], v[172:173], v[20:21], v[18:19] op_sel_hi:[0,1,1]
	v_pk_mul_f32 v[20:21], v[72:73], v[0:1] op_sel_hi:[1,0]
	v_readlane_b32 s0, v255, 1
	v_pk_fma_f32 v[20:21], v[172:173], v[22:23], v[20:21] op_sel_hi:[0,1,1]
	v_pk_mul_f32 v[22:23], v[56:57], v[0:1] op_sel_hi:[1,0]
	v_pk_fma_f32 v[4:5], v[96:97], v[2:3], v[4:5] op_sel_hi:[1,0,1]
	v_pk_fma_f32 v[22:23], v[172:173], v[24:25], v[22:23] op_sel_hi:[0,1,1]
	v_pk_mul_f32 v[24:25], v[74:75], v[0:1] op_sel_hi:[1,0]
	v_pk_fma_f32 v[6:7], v[80:81], v[2:3], v[6:7] op_sel_hi:[1,0,1]
	v_pk_fma_f32 v[24:25], v[172:173], v[32:33], v[24:25] op_sel_hi:[0,1,1]
	v_pk_mul_f32 v[32:33], v[58:59], v[0:1] op_sel_hi:[1,0]
	v_pk_fma_f32 v[8:9], v[98:99], v[2:3], v[8:9] op_sel_hi:[1,0,1]
	v_pk_fma_f32 v[26:27], v[172:173], v[26:27], v[32:33] op_sel_hi:[0,1,1]
	v_pk_mul_f32 v[32:33], v[76:77], v[0:1] op_sel_hi:[1,0]
	v_pk_fma_f32 v[10:11], v[82:83], v[2:3], v[10:11] op_sel_hi:[1,0,1]
	v_pk_fma_f32 v[32:33], v[172:173], v[34:35], v[32:33] op_sel_hi:[0,1,1]
	v_pk_mul_f32 v[34:35], v[60:61], v[0:1] op_sel_hi:[1,0]
	v_pk_fma_f32 v[12:13], v[100:101], v[2:3], v[12:13] op_sel_hi:[1,0,1]
	v_pk_fma_f32 v[28:29], v[172:173], v[28:29], v[34:35] op_sel_hi:[0,1,1]
	v_pk_mul_f32 v[34:35], v[78:79], v[0:1] op_sel_hi:[1,0]
	v_pk_fma_f32 v[14:15], v[84:85], v[2:3], v[14:15] op_sel_hi:[1,0,1]
	v_pk_fma_f32 v[34:35], v[172:173], v[36:37], v[34:35] op_sel_hi:[0,1,1]
	v_pk_mul_f32 v[36:37], v[62:63], v[0:1] op_sel_hi:[1,0]
	v_pk_fma_f32 v[16:17], v[102:103], v[2:3], v[16:17] op_sel_hi:[1,0,1]
	v_pk_fma_f32 v[30:31], v[172:173], v[30:31], v[36:37] op_sel_hi:[0,1,1]
	v_pk_fma_f32 v[18:19], v[86:87], v[2:3], v[18:19] op_sel_hi:[1,0,1]
	v_pk_fma_f32 v[20:21], v[104:105], v[2:3], v[20:21] op_sel_hi:[1,0,1]
	v_pk_fma_f32 v[22:23], v[88:89], v[2:3], v[22:23] op_sel_hi:[1,0,1]
	v_pk_fma_f32 v[24:25], v[106:107], v[2:3], v[24:25] op_sel_hi:[1,0,1]
	v_pk_fma_f32 v[26:27], v[90:91], v[2:3], v[26:27] op_sel_hi:[1,0,1]
	v_pk_fma_f32 v[32:33], v[108:109], v[2:3], v[32:33] op_sel_hi:[1,0,1]
	v_pk_fma_f32 v[28:29], v[92:93], v[2:3], v[28:29] op_sel_hi:[1,0,1]
	v_pk_fma_f32 v[34:35], v[110:111], v[2:3], v[34:35] op_sel_hi:[1,0,1]
	v_pk_fma_f32 v[2:3], v[94:95], v[2:3], v[30:31] op_sel_hi:[1,0,1]
	v_lshlrev_b64 v[30:31], 11, v[186:187]
	v_readlane_b32 s1, v255, 2
	v_lshlrev_b32_e32 v0, 1, v189
	v_cvt_pk_bf16_f32 v4, v4, v5
	v_lshl_add_u64 v[30:31], s[0:1], 0, v[30:31]
	v_lshl_add_u64 v[30:31], v[30:31], 0, v[0:1]
	v_lshlrev_b32_e32 v0, 3, v191
	v_lshl_add_u64 v[30:31], v[30:31], 0, v[0:1]
	s_mov_b64 s[0:1], 0x8a00400
	v_lshl_add_u64 v[36:37], v[30:31], 0, s[0:1]
	s_mov_b32 s0, 0x8a00000
	v_cvt_pk_bf16_f32 v5, v8, v9
	v_add_co_u32_e32 v8, vcc, s0, v30
	v_cvt_pk_bf16_f32 v6, v6, v7
	s_nop 0
	v_addc_co_u32_e32 v9, vcc, 0, v31, vcc
	v_cvt_pk_bf16_f32 v7, v10, v11
	s_mov_b64 s[98:99], exec
	s_mov_b32 exec_lo, s32
	s_mov_b32 exec_hi, 0
	v_mov_b32_e32 v253, 1
	global_atomic_add v252, v1, v253, s[30:31] sc0
	s_mov_b64 exec, s[98:99]
	v_mov_b32_e32 v240, v4
	v_mov_b32_e32 v241, v5
	v_mov_b32_e32 v244, v6
	v_mov_b32_e32 v245, v7
	v_cvt_pk_bf16_f32 v4, v12, v13
	v_cvt_pk_bf16_f32 v5, v16, v17
	v_cvt_pk_bf16_f32 v6, v14, v15
	v_cvt_pk_bf16_f32 v7, v18, v19
	v_mov_b32_e32 v242, v4
	v_mov_b32_e32 v243, v5
	v_mbcnt_lo_u32_b32 v222, -1, 0
	v_mbcnt_hi_u32_b32 v222, -1, v222
	v_lshrrev_b32_e32 v222, 5, v222
	v_lshlrev_b32_e32 v222, 3, v222
	v_mov_b32_e32 v223, 0
	v_permlane32_swap_b32_e32 v240, v242
	v_permlane32_swap_b32_e32 v241, v243
	v_lshl_add_u64 v[222:223], v[36:37], 0, v[222:223]
	global_store_dwordx4 v[222:223], v[240:243], off sc1
	v_mov_b32_e32 v246, v6
	v_mov_b32_e32 v247, v7
	v_mbcnt_lo_u32_b32 v222, -1, 0
	v_mbcnt_hi_u32_b32 v222, -1, v222
	v_lshrrev_b32_e32 v222, 5, v222
	v_lshlrev_b32_e32 v222, 3, v222
	v_mov_b32_e32 v223, 0
	v_permlane32_swap_b32_e32 v244, v246
	v_permlane32_swap_b32_e32 v245, v247
	v_lshl_add_u64 v[222:223], v[36:37], 0, v[222:223]
	global_store_dwordx4 v[222:223], v[244:247], off offset:64 sc1
	v_cvt_pk_bf16_f32 v4, v20, v21
	v_cvt_pk_bf16_f32 v5, v24, v25
	v_cvt_pk_bf16_f32 v6, v22, v23
	v_cvt_pk_bf16_f32 v7, v26, v27
	v_mov_b32_e32 v240, v4
	v_mov_b32_e32 v241, v5
	v_mov_b32_e32 v244, v6
	v_mov_b32_e32 v245, v7
	v_cvt_pk_bf16_f32 v4, v32, v33
	v_cvt_pk_bf16_f32 v5, v34, v35
	s_mov_b64 s[4:5], 0
	v_cvt_pk_bf16_f32 v6, v28, v29
	v_cvt_pk_bf16_f32 v7, v2, v3
	v_mov_b32_e32 v242, v4
	v_mov_b32_e32 v243, v5
	v_mbcnt_lo_u32_b32 v222, -1, 0
	v_mbcnt_hi_u32_b32 v222, -1, v222
	v_lshrrev_b32_e32 v222, 5, v222
	v_lshlrev_b32_e32 v222, 3, v222
	v_mov_b32_e32 v223, 0
	v_permlane32_swap_b32_e32 v240, v242
	v_permlane32_swap_b32_e32 v241, v243
	v_lshl_add_u64 v[222:223], v[36:37], 0, v[222:223]
	global_store_dwordx4 v[222:223], v[240:243], off offset:32 sc1
	v_mov_b32_e32 v246, v6
	v_mov_b32_e32 v247, v7
	v_mbcnt_lo_u32_b32 v222, -1, 0
	v_mbcnt_hi_u32_b32 v222, -1, v222
	v_lshrrev_b32_e32 v222, 5, v222
	v_lshlrev_b32_e32 v222, 3, v222
	v_mov_b32_e32 v223, 0
	v_permlane32_swap_b32_e32 v244, v246
	v_permlane32_swap_b32_e32 v245, v247
	v_lshl_add_u64 v[222:223], v[36:37], 0, v[222:223]
	global_store_dwordx4 v[222:223], v[244:247], off offset:96 sc1
	s_barrier

.LBB0_1707:
	s_or_b64 exec, exec, s[12:13]
	v_mov_b32_e32 v0, v1
	s_mov_b32 s9, s95
	v_mbcnt_lo_u32_b32 v0, -1, v0
	v_mbcnt_hi_u32_b32 v0, -1, v0
	v_lshlrev_b32_e32 v0, 2, v0
	v_xor_b32_e32 v0, 0x80, v0
	ds_bpermute_b32 v0, v0, v129
	s_waitcnt lgkmcnt(0)
	v_add_f32_e32 v0, v129, v0
	v_max_f32_e32 v0, 0xda24260, v0
	v_div_scale_f32 v2, s[0:1], v0, v0, 1.0
	v_rcp_f32_e32 v3, v2
	s_mov_b64 s[0:1], 0x8a00200
	v_fma_f32 v4, -v2, v3, 1.0
	v_fmac_f32_e32 v3, v4, v3
	v_div_scale_f32 v4, vcc, 1.0, v0, 1.0
	v_mul_f32_e32 v5, v4, v3
	v_fma_f32 v6, -v2, v5, v4
	v_fmac_f32_e32 v5, v6, v3
	v_fma_f32 v2, -v2, v5, v4
	v_div_fmas_f32 v2, v2, v3, v5
	v_lshlrev_b64 v[4:5], 11, v[108:109]
	v_lshl_add_u64 v[4:5], s[6:7], 0, v[4:5]
	v_div_fixup_f32 v2, v2, v0, 1.0
	v_lshl_add_u64 v[4:5], v[4:5], 0, s[8:9]
	v_lshlrev_b32_e32 v0, 1, v111
	v_lshl_add_u64 v[4:5], v[4:5], 0, v[0:1]
	v_lshl_add_u64 v[6:7], v[4:5], 0, s[0:1]
	s_mov_b32 s0, 0x8a00000
	v_pk_mul_f32 v[8:9], v[32:33], v[2:3] op_sel_hi:[1,0]
	v_pk_mul_f32 v[10:11], v[34:35], v[2:3] op_sel_hi:[1,0]
	v_add_co_u32_e32 v4, vcc, s0, v4
	v_cvt_pk_bf16_f32 v8, v8, v9
	v_cvt_pk_bf16_f32 v9, v10, v11
	v_pk_mul_f32 v[10:11], v[16:17], v[2:3] op_sel_hi:[1,0]
	v_pk_mul_f32 v[12:13], v[18:19], v[2:3] op_sel_hi:[1,0]
	v_addc_co_u32_e32 v5, vcc, 0, v5, vcc
	v_cvt_pk_bf16_f32 v10, v10, v11
	v_cvt_pk_bf16_f32 v11, v12, v13
	s_mov_b64 s[98:99], exec
	s_mov_b32 exec_lo, s32
	s_mov_b32 exec_hi, 0
	v_mov_b32_e32 v253, 1
	global_atomic_add v252, v1, v253, s[30:31] sc0
	s_mov_b64 exec, s[98:99]
	v_mov_b32_e32 v240, v8
	v_mov_b32_e32 v241, v9
	v_mov_b32_e32 v244, v10
	v_mov_b32_e32 v245, v11
	v_pk_mul_f32 v[4:5], v[36:37], v[2:3] op_sel_hi:[1,0]
	v_pk_mul_f32 v[8:9], v[38:39], v[2:3] op_sel_hi:[1,0]
	v_cvt_pk_bf16_f32 v4, v4, v5
	v_cvt_pk_bf16_f32 v5, v8, v9
	v_pk_mul_f32 v[8:9], v[20:21], v[2:3] op_sel_hi:[1,0]
	v_pk_mul_f32 v[10:11], v[22:23], v[2:3] op_sel_hi:[1,0]
	v_cvt_pk_bf16_f32 v8, v8, v9
	v_cvt_pk_bf16_f32 v9, v10, v11
	v_mov_b32_e32 v242, v4
	v_mov_b32_e32 v243, v5
	v_mbcnt_lo_u32_b32 v222, -1, 0
	v_mbcnt_hi_u32_b32 v222, -1, v222
	v_lshrrev_b32_e32 v222, 5, v222
	v_lshlrev_b32_e32 v222, 3, v222
	v_mov_b32_e32 v223, 0
	v_permlane32_swap_b32_e32 v240, v242
	v_permlane32_swap_b32_e32 v241, v243
	v_lshl_add_u64 v[222:223], v[6:7], 0, v[222:223]
	global_store_dwordx4 v[222:223], v[240:243], off sc1
	v_mov_b32_e32 v246, v8
	v_mov_b32_e32 v247, v9
	v_mbcnt_lo_u32_b32 v222, -1, 0
	v_mbcnt_hi_u32_b32 v222, -1, v222
	v_lshrrev_b32_e32 v222, 5, v222
	v_lshlrev_b32_e32 v222, 3, v222
	v_mov_b32_e32 v223, 0
	v_permlane32_swap_b32_e32 v244, v246
	v_permlane32_swap_b32_e32 v245, v247
	v_lshl_add_u64 v[222:223], v[6:7], 0, v[222:223]
	global_store_dwordx4 v[222:223], v[244:247], off offset:64 sc1
	v_pk_mul_f32 v[4:5], v[40:41], v[2:3] op_sel_hi:[1,0]
	v_pk_mul_f32 v[8:9], v[42:43], v[2:3] op_sel_hi:[1,0]
	v_cvt_pk_bf16_f32 v4, v4, v5
	v_cvt_pk_bf16_f32 v5, v8, v9
	v_pk_mul_f32 v[8:9], v[24:25], v[2:3] op_sel_hi:[1,0]
	v_pk_mul_f32 v[10:11], v[26:27], v[2:3] op_sel_hi:[1,0]
	v_cvt_pk_bf16_f32 v8, v8, v9
	v_cvt_pk_bf16_f32 v9, v10, v11
	v_mov_b32_e32 v240, v4
	v_mov_b32_e32 v241, v5
	v_mov_b32_e32 v244, v8
	v_mov_b32_e32 v245, v9
	v_pk_mul_f32 v[4:5], v[44:45], v[2:3] op_sel_hi:[1,0]
	v_pk_mul_f32 v[8:9], v[46:47], v[2:3] op_sel_hi:[1,0]
	v_cvt_pk_bf16_f32 v4, v4, v5
	v_cvt_pk_bf16_f32 v5, v8, v9
	v_pk_mul_f32 v[8:9], v[28:29], v[2:3] op_sel_hi:[1,0]
	v_pk_mul_f32 v[2:3], v[30:31], v[2:3] op_sel_hi:[1,0]
	v_cvt_pk_bf16_f32 v8, v8, v9
	v_cvt_pk_bf16_f32 v9, v2, v3
	v_mov_b32_e32 v242, v4
	v_mov_b32_e32 v243, v5
	v_mbcnt_lo_u32_b32 v222, -1, 0
	v_mbcnt_hi_u32_b32 v222, -1, v222
	v_lshrrev_b32_e32 v222, 5, v222
	v_lshlrev_b32_e32 v222, 3, v222
	v_mov_b32_e32 v223, 0
	v_permlane32_swap_b32_e32 v240, v242
	v_permlane32_swap_b32_e32 v241, v243
	v_lshl_add_u64 v[222:223], v[6:7], 0, v[222:223]
	global_store_dwordx4 v[222:223], v[240:243], off offset:32 sc1
	v_mov_b32_e32 v246, v8
	v_mov_b32_e32 v247, v9
	v_mbcnt_lo_u32_b32 v222, -1, 0
	v_mbcnt_hi_u32_b32 v222, -1, v222
	v_lshrrev_b32_e32 v222, 5, v222
	v_lshlrev_b32_e32 v222, 3, v222
	v_mov_b32_e32 v223, 0
	v_permlane32_swap_b32_e32 v244, v246
	v_permlane32_swap_b32_e32 v245, v247
	v_lshl_add_u64 v[222:223], v[6:7], 0, v[222:223]
	global_store_dwordx4 v[222:223], v[244:247], off offset:96 sc1
	s_barrier

.LBB0_1742:
	s_or_b64 exec, exec, s[0:1]
	v_lshlrev_b64 v[18:19], 11, v[92:93]
	v_lshl_add_u64 v[18:19], s[16:17], 0, v[18:19]
	v_lshlrev_b32_e32 v20, 2, v85
	v_lshl_add_u64 v[18:19], v[18:19], 0, s[94:95]
	v_lshl_add_u64 v[18:19], v[18:19], 0, v[0:1]
	v_lshlrev_b32_e32 v0, 1, v20
	s_waitcnt vmcnt(3)
	v_lshlrev_b32_e32 v22, 16, v94
	v_and_b32_e32 v23, 0xffff0000, v94
	s_nop 1
	v_pk_add_f32 v[2:3], v[84:85], v[2:3] op_sel_hi:[0,1]
	v_lshl_add_u64 v[18:19], v[18:19], 0, v[0:1]
	s_mov_b64 s[0:1], 0x8a00600
	v_pk_mul_f32 v[2:3], v[2:3], v[22:23]
	v_lshlrev_b32_e32 v22, 16, v95
	v_and_b32_e32 v23, 0xffff0000, v95
	v_pk_add_f32 v[4:5], v[84:85], v[4:5] op_sel_hi:[0,1]
	v_lshl_add_u64 v[20:21], v[18:19], 0, s[0:1]
	v_pk_mul_f32 v[4:5], v[4:5], v[22:23]
	s_mov_b32 s0, 0x8a00000
	v_cvt_pk_bf16_f32 v2, v2, v3
	v_cvt_pk_bf16_f32 v3, v4, v5
	v_add_co_u32_e32 v4, vcc, s0, v18
	s_nop 1
	v_addc_co_u32_e32 v5, vcc, 0, v19, vcc
	s_mov_b64 s[98:99], exec
	s_mov_b32 exec_lo, s32
	s_mov_b32 exec_hi, 0
	v_mov_b32_e32 v253, 1
	global_atomic_add v252, v1, v253, s[30:31] sc0
	s_mov_b64 exec, s[98:99]
	v_mov_b32_e32 v240, v2
	v_mov_b32_e32 v241, v3
	s_waitcnt vmcnt(2)
	v_lshlrev_b32_e32 v2, 16, v90
	v_and_b32_e32 v3, 0xffff0000, v90
	v_pk_add_f32 v[4:5], v[84:85], v[6:7] op_sel_hi:[0,1]
	v_pk_mul_f32 v[2:3], v[4:5], v[2:3]
	v_lshlrev_b32_e32 v4, 16, v91
	v_and_b32_e32 v5, 0xffff0000, v91
	v_pk_add_f32 v[6:7], v[84:85], v[8:9] op_sel_hi:[0,1]
	v_pk_mul_f32 v[4:5], v[6:7], v[4:5]
	v_cvt_pk_bf16_f32 v2, v2, v3
	v_cvt_pk_bf16_f32 v3, v4, v5
	v_mov_b32_e32 v242, v2
	v_mov_b32_e32 v243, v3
	v_mbcnt_lo_u32_b32 v222, -1, 0
	v_mbcnt_hi_u32_b32 v222, -1, v222
	v_lshrrev_b32_e32 v222, 5, v222
	v_lshlrev_b32_e32 v222, 3, v222
	v_mov_b32_e32 v223, 0
	v_permlane32_swap_b32_e32 v240, v242
	v_permlane32_swap_b32_e32 v241, v243
	v_lshl_add_u64 v[222:223], v[20:21], 0, v[222:223]
	global_store_dwordx4 v[222:223], v[240:243], off sc1
	s_waitcnt vmcnt(2)
	v_lshlrev_b32_e32 v2, 16, v88
	v_and_b32_e32 v3, 0xffff0000, v88
	v_pk_add_f32 v[4:5], v[84:85], v[10:11] op_sel_hi:[0,1]
	v_pk_mul_f32 v[2:3], v[4:5], v[2:3]
	v_lshlrev_b32_e32 v4, 16, v89
	v_and_b32_e32 v5, 0xffff0000, v89
	v_pk_add_f32 v[6:7], v[84:85], v[12:13] op_sel_hi:[0,1]
	v_pk_mul_f32 v[4:5], v[6:7], v[4:5]
	v_cvt_pk_bf16_f32 v2, v2, v3
	v_cvt_pk_bf16_f32 v3, v4, v5
	v_mov_b32_e32 v240, v2
	v_mov_b32_e32 v241, v3
	s_waitcnt vmcnt(1)
	v_lshlrev_b32_e32 v2, 16, v86
	v_and_b32_e32 v3, 0xffff0000, v86
	v_pk_add_f32 v[4:5], v[84:85], v[14:15] op_sel_hi:[0,1]
	v_pk_mul_f32 v[2:3], v[4:5], v[2:3]
	v_lshlrev_b32_e32 v4, 16, v87
	v_and_b32_e32 v5, 0xffff0000, v87
	v_pk_add_f32 v[6:7], v[84:85], v[16:17] op_sel_hi:[0,1]
	v_pk_mul_f32 v[4:5], v[6:7], v[4:5]
	v_cvt_pk_bf16_f32 v2, v2, v3
	v_cvt_pk_bf16_f32 v3, v4, v5
	v_mov_b32_e32 v242, v2
	v_mov_b32_e32 v243, v3
	v_mbcnt_lo_u32_b32 v222, -1, 0
	v_mbcnt_hi_u32_b32 v222, -1, v222
	v_lshrrev_b32_e32 v222, 5, v222
	v_lshlrev_b32_e32 v222, 3, v222
	v_mov_b32_e32 v223, 0
	v_permlane32_swap_b32_e32 v240, v242
	v_permlane32_swap_b32_e32 v241, v243
	v_lshl_add_u64 v[222:223], v[20:21], 0, v[222:223]
	global_store_dwordx4 v[222:223], v[240:243], off offset:32 sc1
	s_barrier
	s_branch .LBB0_1771

.LBB0_1754:
	v_mov_b32_e32 v0, v1
	s_lshl_b32 s94, s3, 1
	v_mbcnt_lo_u32_b32 v0, -1, v0
	v_mbcnt_hi_u32_b32 v0, -1, v0
	v_lshlrev_b32_e32 v0, 2, v0
	v_xor_b32_e32 v0, 0x80, v0
	ds_bpermute_b32 v0, v0, v189
	s_waitcnt lgkmcnt(0)
	v_add_f32_e32 v0, v189, v0
	v_max_f32_e32 v0, 0xda24260, v0
	v_div_scale_f32 v66, s[0:1], v0, v0, 1.0
	v_rcp_f32_e32 v67, v66
	s_nop 0
	v_fma_f32 v68, -v66, v67, 1.0
	v_fmac_f32_e32 v67, v68, v67
	v_div_scale_f32 v68, vcc, 1.0, v0, 1.0
	v_mul_f32_e32 v69, v68, v67
	v_fma_f32 v70, -v66, v69, v68
	v_fmac_f32_e32 v69, v70, v67
	v_fma_f32 v66, -v66, v69, v68
	v_div_fmas_f32 v66, v66, v67, v69
	v_div_fixup_f32 v66, v66, v0, 1.0
	v_mov_b32_e32 v0, v1
	s_nop 0
	v_mbcnt_lo_u32_b32 v0, -1, v0
	v_mbcnt_hi_u32_b32 v0, -1, v0
	v_lshlrev_b32_e32 v0, 2, v0
	v_xor_b32_e32 v0, 0x80, v0
	ds_bpermute_b32 v0, v0, v159
	s_waitcnt lgkmcnt(0)
	v_add_f32_e32 v0, v159, v0
	v_max_f32_e32 v0, 0xda24260, v0
	v_div_scale_f32 v67, s[0:1], v0, v0, v175
	v_rcp_f32_e32 v68, v67
	s_mov_b64 s[0:1], 0x8a00000
	v_fma_f32 v69, -v67, v68, 1.0
	v_fmac_f32_e32 v68, v69, v68
	v_div_scale_f32 v69, vcc, v175, v0, v175
	v_mul_f32_e32 v70, v69, v68
	v_fma_f32 v71, -v67, v70, v69
	v_fmac_f32_e32 v70, v71, v68
	v_fma_f32 v67, -v67, v70, v69
	v_div_fmas_f32 v67, v67, v68, v70
	v_div_fixup_f32 v68, v67, v0, v175
	v_mov_b32_e32 v0, v1
	v_pk_mul_f32 v[44:45], v[44:45], v[68:69] op_sel_hi:[1,0]
	v_mbcnt_lo_u32_b32 v0, -1, v0
	v_pk_mul_f32 v[52:53], v[52:53], v[68:69] op_sel_hi:[1,0]
	v_pk_mul_f32 v[50:51], v[50:51], v[68:69] op_sel_hi:[1,0]
	v_pk_fma_f32 v[28:29], v[28:29], v[66:67], v[44:45] op_sel_hi:[1,0,1] neg_lo:[0,0,1] neg_hi:[0,0,1]
	v_pk_mul_f32 v[44:45], v[60:61], v[68:69] op_sel_hi:[1,0]
	v_mbcnt_hi_u32_b32 v0, -1, v0
	v_lshlrev_b64 v[60:61], 11, v[154:155]
	v_pk_fma_f32 v[4:5], v[4:5], v[66:67], v[52:53] op_sel_hi:[1,0,1] neg_lo:[0,0,1] neg_hi:[0,0,1]
	v_pk_fma_f32 v[2:3], v[2:3], v[66:67], v[50:51] op_sel_hi:[1,0,1] neg_lo:[0,0,1] neg_hi:[0,0,1]
	v_pk_mul_f32 v[36:37], v[36:37], v[68:69] op_sel_hi:[1,0]
	v_pk_mul_f32 v[34:35], v[34:35], v[68:69] op_sel_hi:[1,0]
	v_pk_mul_f32 v[48:49], v[48:49], v[68:69] op_sel_hi:[1,0]
	v_lshlrev_b32_e32 v0, 2, v0
	v_lshl_add_u64 v[60:61], s[4:5], 0, v[60:61]
	v_pk_mul_f32 v[52:53], v[4:5], v[4:5]
	v_pk_mul_f32 v[50:51], v[2:3], v[2:3]
	v_pk_fma_f32 v[20:21], v[20:21], v[66:67], v[36:37] op_sel_hi:[1,0,1] neg_lo:[0,0,1] neg_hi:[0,0,1]
	v_pk_fma_f32 v[18:19], v[18:19], v[66:67], v[34:35] op_sel_hi:[1,0,1] neg_lo:[0,0,1] neg_hi:[0,0,1]
	v_pk_fma_f32 v[32:33], v[32:33], v[66:67], v[48:49] op_sel_hi:[1,0,1] neg_lo:[0,0,1] neg_hi:[0,0,1]
	v_pk_mul_f32 v[48:49], v[64:65], v[68:69] op_sel_hi:[1,0]
	v_xor_b32_e32 v64, 0x80, v0
	v_lshl_add_u64 v[60:61], v[60:61], 0, s[94:95]
	v_lshlrev_b32_e32 v0, 1, v157
	v_pk_fma_f32 v[36:37], v[20:21], v[20:21], v[52:53]
	v_pk_fma_f32 v[34:35], v[18:19], v[18:19], v[50:51]
	v_pk_mul_f32 v[52:53], v[54:55], v[68:69] op_sel_hi:[1,0]
	v_lshl_add_u64 v[60:61], v[60:61], 0, v[0:1]
	v_pk_mul_f32 v[50:51], v[56:57], v[68:69] op_sel_hi:[1,0]
	v_pk_fma_f32 v[6:7], v[6:7], v[66:67], v[52:53] op_sel_hi:[1,0,1] neg_lo:[0,0,1] neg_hi:[0,0,1]
	v_pk_mul_f32 v[38:39], v[38:39], v[68:69] op_sel_hi:[1,0]
	v_add_f32_e32 v0, v34, v35
	v_pk_fma_f32 v[8:9], v[8:9], v[66:67], v[50:51] op_sel_hi:[1,0,1] neg_lo:[0,0,1] neg_hi:[0,0,1]
	v_pk_mul_f32 v[52:53], v[6:7], v[6:7]
	v_pk_mul_f32 v[40:41], v[40:41], v[68:69] op_sel_hi:[1,0]
	v_pk_fma_f32 v[22:23], v[22:23], v[66:67], v[38:39] op_sel_hi:[1,0,1] neg_lo:[0,0,1] neg_hi:[0,0,1]
	v_add_f32_e32 v0, v36, v0
	v_pk_mul_f32 v[50:51], v[8:9], v[8:9]
	v_pk_fma_f32 v[24:25], v[24:25], v[66:67], v[40:41] op_sel_hi:[1,0,1] neg_lo:[0,0,1] neg_hi:[0,0,1]
	v_pk_fma_f32 v[38:39], v[22:23], v[22:23], v[52:53]
	v_add_f32_e32 v0, v37, v0
	v_pk_fma_f32 v[40:41], v[24:25], v[24:25], v[50:51]
	v_pk_mul_f32 v[50:51], v[58:59], v[68:69] op_sel_hi:[1,0]
	v_add_f32_e32 v0, v38, v0
	v_pk_fma_f32 v[10:11], v[10:11], v[66:67], v[50:51] op_sel_hi:[1,0,1] neg_lo:[0,0,1] neg_hi:[0,0,1]
	v_pk_mul_f32 v[42:43], v[42:43], v[68:69] op_sel_hi:[1,0]
	v_add_f32_e32 v0, v39, v0
	v_pk_mul_f32 v[50:51], v[10:11], v[10:11]
	v_pk_fma_f32 v[26:27], v[26:27], v[66:67], v[42:43] op_sel_hi:[1,0,1] neg_lo:[0,0,1] neg_hi:[0,0,1]
	v_add_f32_e32 v0, v40, v0
	v_pk_fma_f32 v[12:13], v[12:13], v[66:67], v[44:45] op_sel_hi:[1,0,1] neg_lo:[0,0,1] neg_hi:[0,0,1]
	v_pk_mul_f32 v[46:47], v[46:47], v[68:69] op_sel_hi:[1,0]
	v_pk_fma_f32 v[42:43], v[26:27], v[26:27], v[50:51]
	v_add_f32_e32 v0, v41, v0
	v_pk_mul_f32 v[44:45], v[12:13], v[12:13]
	v_pk_fma_f32 v[30:31], v[30:31], v[66:67], v[46:47] op_sel_hi:[1,0,1] neg_lo:[0,0,1] neg_hi:[0,0,1]
	v_pk_mul_f32 v[46:47], v[62:63], v[68:69] op_sel_hi:[1,0]
	v_add_f32_e32 v0, v42, v0
	v_pk_fma_f32 v[44:45], v[28:29], v[28:29], v[44:45]
	v_pk_fma_f32 v[14:15], v[14:15], v[66:67], v[46:47] op_sel_hi:[1,0,1] neg_lo:[0,0,1] neg_hi:[0,0,1]
	v_add_f32_e32 v0, v43, v0
	v_pk_mul_f32 v[46:47], v[14:15], v[14:15]
	v_add_f32_e32 v0, v44, v0
	v_pk_fma_f32 v[46:47], v[30:31], v[30:31], v[46:47]
	v_pk_fma_f32 v[16:17], v[16:17], v[66:67], v[48:49] op_sel_hi:[1,0,1] neg_lo:[0,0,1] neg_hi:[0,0,1]
	v_add_f32_e32 v0, v45, v0
	v_pk_mul_f32 v[48:49], v[16:17], v[16:17]
	v_add_f32_e32 v0, v46, v0
	v_pk_fma_f32 v[48:49], v[32:33], v[32:33], v[48:49]
	v_add_f32_e32 v0, v47, v0
	v_add_f32_e32 v0, v48, v0
	v_add_f32_e32 v0, v49, v0
	ds_bpermute_b32 v34, v64, v0
	v_lshl_add_u64 v[62:63], v[60:61], 0, s[0:1]
	s_mov_b32 s0, 0x8a00000
	s_waitcnt lgkmcnt(0)
	v_add_f32_e32 v0, v0, v34
	v_fmamk_f32 v0, v0, 0x3c800000, v228
	v_rsq_f32_e32 v0, v0
	s_nop 0
	v_mul_f32_e32 v0, v185, v0
	v_pk_mul_f32 v[2:3], v[2:3], v[0:1] op_sel_hi:[1,0]
	v_pk_mul_f32 v[4:5], v[4:5], v[0:1] op_sel_hi:[1,0]
	v_pk_mul_f32 v[18:19], v[18:19], v[0:1] op_sel_hi:[1,0]
	v_pk_mul_f32 v[20:21], v[20:21], v[0:1] op_sel_hi:[1,0]
	v_cvt_pk_bf16_f32 v2, v2, v3
	v_cvt_pk_bf16_f32 v3, v4, v5
	v_add_co_u32_e32 v4, vcc, s0, v60
	v_cvt_pk_bf16_f32 v18, v18, v19
	v_cvt_pk_bf16_f32 v19, v20, v21
	v_addc_co_u32_e32 v5, vcc, 0, v61, vcc
	s_mov_b64 s[98:99], exec
	s_mov_b32 exec_lo, s32
	s_mov_b32 exec_hi, 0
	v_mov_b32_e32 v253, 1
	global_atomic_add v252, v1, v253, s[30:31] sc0
	s_mov_b64 exec, s[98:99]
	v_mov_b32_e32 v240, v18
	v_mov_b32_e32 v241, v19
	v_mov_b32_e32 v244, v2
	v_mov_b32_e32 v245, v3
	v_pk_mul_f32 v[2:3], v[22:23], v[0:1] op_sel_hi:[1,0]
	v_pk_mul_f32 v[4:5], v[24:25], v[0:1] op_sel_hi:[1,0]
	v_cvt_pk_bf16_f32 v2, v2, v3
	v_cvt_pk_bf16_f32 v3, v4, v5
	v_pk_mul_f32 v[4:5], v[6:7], v[0:1] op_sel_hi:[1,0]
	v_pk_mul_f32 v[6:7], v[8:9], v[0:1] op_sel_hi:[1,0]
	v_cvt_pk_bf16_f32 v4, v4, v5
	v_cvt_pk_bf16_f32 v5, v6, v7
	v_mov_b32_e32 v242, v2
	v_mov_b32_e32 v243, v3
	v_mbcnt_lo_u32_b32 v222, -1, 0
	v_mbcnt_hi_u32_b32 v222, -1, v222
	v_lshrrev_b32_e32 v222, 5, v222
	v_lshlrev_b32_e32 v222, 3, v222
	v_mov_b32_e32 v223, 0
	v_permlane32_swap_b32_e32 v240, v242
	v_permlane32_swap_b32_e32 v241, v243
	v_lshl_add_u64 v[222:223], v[62:63], 0, v[222:223]
	global_store_dwordx4 v[222:223], v[240:243], off sc1
	v_mov_b32_e32 v246, v4
	v_mov_b32_e32 v247, v5
	v_mbcnt_lo_u32_b32 v222, -1, 0
	v_mbcnt_hi_u32_b32 v222, -1, v222
	v_lshrrev_b32_e32 v222, 5, v222
	v_lshlrev_b32_e32 v222, 3, v222
	v_mov_b32_e32 v223, 0
	v_permlane32_swap_b32_e32 v244, v246
	v_permlane32_swap_b32_e32 v245, v247
	v_lshl_add_u64 v[222:223], v[62:63], 0, v[222:223]
	global_store_dwordx4 v[222:223], v[244:247], off offset:64 sc1
	v_pk_mul_f32 v[2:3], v[26:27], v[0:1] op_sel_hi:[1,0]
	v_pk_mul_f32 v[4:5], v[28:29], v[0:1] op_sel_hi:[1,0]
	v_cvt_pk_bf16_f32 v2, v2, v3
	v_cvt_pk_bf16_f32 v3, v4, v5
	v_pk_mul_f32 v[4:5], v[10:11], v[0:1] op_sel_hi:[1,0]
	v_pk_mul_f32 v[6:7], v[12:13], v[0:1] op_sel_hi:[1,0]
	v_cvt_pk_bf16_f32 v4, v4, v5
	v_cvt_pk_bf16_f32 v5, v6, v7
	v_mov_b32_e32 v240, v2
	v_mov_b32_e32 v241, v3
	v_mov_b32_e32 v244, v4
	v_mov_b32_e32 v245, v5
	v_pk_mul_f32 v[2:3], v[30:31], v[0:1] op_sel_hi:[1,0]
	v_pk_mul_f32 v[4:5], v[32:33], v[0:1] op_sel_hi:[1,0]
	v_cvt_pk_bf16_f32 v2, v2, v3
	v_cvt_pk_bf16_f32 v3, v4, v5
	v_pk_mul_f32 v[4:5], v[14:15], v[0:1] op_sel_hi:[1,0]
	v_pk_mul_f32 v[6:7], v[16:17], v[0:1] op_sel_hi:[1,0]
	v_cvt_pk_bf16_f32 v4, v4, v5
	v_cvt_pk_bf16_f32 v5, v6, v7
	v_mov_b32_e32 v242, v2
	v_mov_b32_e32 v243, v3
	v_mbcnt_lo_u32_b32 v222, -1, 0
	v_mbcnt_hi_u32_b32 v222, -1, v222
	v_lshrrev_b32_e32 v222, 5, v222
	v_lshlrev_b32_e32 v222, 3, v222
	v_mov_b32_e32 v223, 0
	v_permlane32_swap_b32_e32 v240, v242
	v_permlane32_swap_b32_e32 v241, v243
	v_lshl_add_u64 v[222:223], v[62:63], 0, v[222:223]
	global_store_dwordx4 v[222:223], v[240:243], off offset:32 sc1
	v_mov_b32_e32 v246, v4
	v_mov_b32_e32 v247, v5
	v_mbcnt_lo_u32_b32 v222, -1, 0
	v_mbcnt_hi_u32_b32 v222, -1, v222
	v_lshrrev_b32_e32 v222, 5, v222
	v_lshlrev_b32_e32 v222, 3, v222
	v_mov_b32_e32 v223, 0
	v_permlane32_swap_b32_e32 v244, v246
	v_permlane32_swap_b32_e32 v245, v247
	v_lshl_add_u64 v[222:223], v[62:63], 0, v[222:223]
	global_store_dwordx4 v[222:223], v[244:247], off offset:96 sc1
	s_barrier
	s_mov_b64 s[0:1], 0

.LBB0_1770:
	v_mov_b32_e32 v0, v1
	s_lshl_b32 s94, s8, 1
	v_mbcnt_lo_u32_b32 v0, -1, v0
	v_mbcnt_hi_u32_b32 v0, -1, v0
	v_lshlrev_b32_e32 v0, 2, v0
	v_xor_b32_e32 v0, 0x80, v0
	ds_bpermute_b32 v0, v0, v189
	s_waitcnt lgkmcnt(0)
	v_add_f32_e32 v0, v189, v0
	v_max_f32_e32 v0, 0xda24260, v0
	v_div_scale_f32 v66, s[0:1], v0, v0, 1.0
	v_rcp_f32_e32 v67, v66
	s_nop 0
	v_fma_f32 v68, -v66, v67, 1.0
	v_fmac_f32_e32 v67, v68, v67
	v_div_scale_f32 v68, vcc, 1.0, v0, 1.0
	v_mul_f32_e32 v69, v68, v67
	v_fma_f32 v70, -v66, v69, v68
	v_fmac_f32_e32 v69, v70, v67
	v_fma_f32 v66, -v66, v69, v68
	v_div_fmas_f32 v66, v66, v67, v69
	v_div_fixup_f32 v66, v66, v0, 1.0
	v_mov_b32_e32 v0, v1
	s_nop 0
	v_mbcnt_lo_u32_b32 v0, -1, v0
	v_mbcnt_hi_u32_b32 v0, -1, v0
	v_lshlrev_b32_e32 v0, 2, v0
	v_xor_b32_e32 v0, 0x80, v0
	ds_bpermute_b32 v0, v0, v159
	s_waitcnt lgkmcnt(0)
	v_add_f32_e32 v0, v159, v0
	v_max_f32_e32 v0, 0xda24260, v0
	v_div_scale_f32 v67, s[0:1], v0, v0, v175
	v_rcp_f32_e32 v68, v67
	s_mov_b64 s[0:1], 0x8a00000
	v_fma_f32 v69, -v67, v68, 1.0
	v_fmac_f32_e32 v68, v69, v68
	v_div_scale_f32 v69, vcc, v175, v0, v175
	v_mul_f32_e32 v70, v69, v68
	v_fma_f32 v71, -v67, v70, v69
	v_fmac_f32_e32 v70, v71, v68
	v_fma_f32 v67, -v67, v70, v69
	v_div_fmas_f32 v67, v67, v68, v70
	v_div_fixup_f32 v68, v67, v0, v175
	v_mov_b32_e32 v0, v1
	v_pk_mul_f32 v[28:29], v[28:29], v[68:69] op_sel_hi:[1,0]
	v_mbcnt_lo_u32_b32 v0, -1, v0
	v_pk_mul_f32 v[52:53], v[52:53], v[68:69] op_sel_hi:[1,0]
	v_pk_mul_f32 v[50:51], v[50:51], v[68:69] op_sel_hi:[1,0]
	v_pk_fma_f32 v[28:29], v[44:45], v[66:67], v[28:29] op_sel_hi:[1,0,1] neg_lo:[0,0,1] neg_hi:[0,0,1]
	v_pk_mul_f32 v[44:45], v[60:61], v[68:69] op_sel_hi:[1,0]
	v_mbcnt_hi_u32_b32 v0, -1, v0
	v_lshlrev_b64 v[60:61], 11, v[154:155]
	v_pk_fma_f32 v[4:5], v[4:5], v[66:67], v[52:53] op_sel_hi:[1,0,1] neg_lo:[0,0,1] neg_hi:[0,0,1]
	v_pk_fma_f32 v[2:3], v[2:3], v[66:67], v[50:51] op_sel_hi:[1,0,1] neg_lo:[0,0,1] neg_hi:[0,0,1]
	v_pk_mul_f32 v[20:21], v[20:21], v[68:69] op_sel_hi:[1,0]
	v_pk_mul_f32 v[18:19], v[18:19], v[68:69] op_sel_hi:[1,0]
	v_pk_mul_f32 v[32:33], v[32:33], v[68:69] op_sel_hi:[1,0]
	v_lshlrev_b32_e32 v0, 2, v0
	v_lshl_add_u64 v[60:61], s[2:3], 0, v[60:61]
	v_pk_mul_f32 v[52:53], v[4:5], v[4:5]
	v_pk_mul_f32 v[50:51], v[2:3], v[2:3]
	v_pk_fma_f32 v[20:21], v[36:37], v[66:67], v[20:21] op_sel_hi:[1,0,1] neg_lo:[0,0,1] neg_hi:[0,0,1]
	v_pk_fma_f32 v[18:19], v[34:35], v[66:67], v[18:19] op_sel_hi:[1,0,1] neg_lo:[0,0,1] neg_hi:[0,0,1]
	v_pk_fma_f32 v[32:33], v[48:49], v[66:67], v[32:33] op_sel_hi:[1,0,1] neg_lo:[0,0,1] neg_hi:[0,0,1]
	v_pk_mul_f32 v[48:49], v[64:65], v[68:69] op_sel_hi:[1,0]
	v_xor_b32_e32 v64, 0x80, v0
	v_lshl_add_u64 v[60:61], v[60:61], 0, s[94:95]
	v_lshlrev_b32_e32 v0, 1, v157
	v_pk_fma_f32 v[36:37], v[20:21], v[20:21], v[52:53]
	v_pk_fma_f32 v[34:35], v[18:19], v[18:19], v[50:51]
	v_pk_mul_f32 v[52:53], v[54:55], v[68:69] op_sel_hi:[1,0]
	v_lshl_add_u64 v[60:61], v[60:61], 0, v[0:1]
	v_pk_mul_f32 v[50:51], v[56:57], v[68:69] op_sel_hi:[1,0]
	v_pk_fma_f32 v[6:7], v[6:7], v[66:67], v[52:53] op_sel_hi:[1,0,1] neg_lo:[0,0,1] neg_hi:[0,0,1]
	v_pk_mul_f32 v[22:23], v[22:23], v[68:69] op_sel_hi:[1,0]
	v_add_f32_e32 v0, v34, v35
	v_pk_fma_f32 v[8:9], v[8:9], v[66:67], v[50:51] op_sel_hi:[1,0,1] neg_lo:[0,0,1] neg_hi:[0,0,1]
	v_pk_mul_f32 v[52:53], v[6:7], v[6:7]
	v_pk_mul_f32 v[24:25], v[24:25], v[68:69] op_sel_hi:[1,0]
	v_pk_fma_f32 v[22:23], v[38:39], v[66:67], v[22:23] op_sel_hi:[1,0,1] neg_lo:[0,0,1] neg_hi:[0,0,1]
	v_add_f32_e32 v0, v36, v0
	v_pk_mul_f32 v[50:51], v[8:9], v[8:9]
	v_pk_fma_f32 v[24:25], v[40:41], v[66:67], v[24:25] op_sel_hi:[1,0,1] neg_lo:[0,0,1] neg_hi:[0,0,1]
	v_pk_fma_f32 v[38:39], v[22:23], v[22:23], v[52:53]
	v_add_f32_e32 v0, v37, v0
	v_pk_fma_f32 v[40:41], v[24:25], v[24:25], v[50:51]
	v_pk_mul_f32 v[50:51], v[58:59], v[68:69] op_sel_hi:[1,0]
	v_add_f32_e32 v0, v38, v0
	v_pk_fma_f32 v[10:11], v[10:11], v[66:67], v[50:51] op_sel_hi:[1,0,1] neg_lo:[0,0,1] neg_hi:[0,0,1]
	v_pk_mul_f32 v[26:27], v[26:27], v[68:69] op_sel_hi:[1,0]
	v_add_f32_e32 v0, v39, v0
	v_pk_mul_f32 v[50:51], v[10:11], v[10:11]
	v_pk_fma_f32 v[26:27], v[42:43], v[66:67], v[26:27] op_sel_hi:[1,0,1] neg_lo:[0,0,1] neg_hi:[0,0,1]
	v_add_f32_e32 v0, v40, v0
	v_pk_fma_f32 v[12:13], v[12:13], v[66:67], v[44:45] op_sel_hi:[1,0,1] neg_lo:[0,0,1] neg_hi:[0,0,1]
	v_pk_mul_f32 v[30:31], v[30:31], v[68:69] op_sel_hi:[1,0]
	v_pk_fma_f32 v[42:43], v[26:27], v[26:27], v[50:51]
	v_add_f32_e32 v0, v41, v0
	v_pk_mul_f32 v[44:45], v[12:13], v[12:13]
	v_pk_fma_f32 v[30:31], v[46:47], v[66:67], v[30:31] op_sel_hi:[1,0,1] neg_lo:[0,0,1] neg_hi:[0,0,1]
	v_pk_mul_f32 v[46:47], v[62:63], v[68:69] op_sel_hi:[1,0]
	v_add_f32_e32 v0, v42, v0
	v_pk_fma_f32 v[44:45], v[28:29], v[28:29], v[44:45]
	v_pk_fma_f32 v[14:15], v[14:15], v[66:67], v[46:47] op_sel_hi:[1,0,1] neg_lo:[0,0,1] neg_hi:[0,0,1]
	v_add_f32_e32 v0, v43, v0
	v_pk_mul_f32 v[46:47], v[14:15], v[14:15]
	v_add_f32_e32 v0, v44, v0
	v_pk_fma_f32 v[46:47], v[30:31], v[30:31], v[46:47]
	v_pk_fma_f32 v[16:17], v[16:17], v[66:67], v[48:49] op_sel_hi:[1,0,1] neg_lo:[0,0,1] neg_hi:[0,0,1]
	v_add_f32_e32 v0, v45, v0
	v_pk_mul_f32 v[48:49], v[16:17], v[16:17]
	v_add_f32_e32 v0, v46, v0
	v_pk_fma_f32 v[48:49], v[32:33], v[32:33], v[48:49]
	v_add_f32_e32 v0, v47, v0
	v_add_f32_e32 v0, v48, v0
	v_add_f32_e32 v0, v49, v0
	ds_bpermute_b32 v34, v64, v0
	v_lshl_add_u64 v[62:63], v[60:61], 0, s[0:1]
	s_mov_b32 s0, 0x8a00000
	s_waitcnt lgkmcnt(0)
	v_add_f32_e32 v0, v0, v34
	v_fmamk_f32 v0, v0, 0x3c800000, v228
	v_rsq_f32_e32 v0, v0
	s_nop 0
	v_mul_f32_e32 v0, v185, v0
	v_pk_mul_f32 v[2:3], v[2:3], v[0:1] op_sel_hi:[1,0]
	v_pk_mul_f32 v[4:5], v[4:5], v[0:1] op_sel_hi:[1,0]
	v_pk_mul_f32 v[18:19], v[18:19], v[0:1] op_sel_hi:[1,0]
	v_pk_mul_f32 v[20:21], v[20:21], v[0:1] op_sel_hi:[1,0]
	v_cvt_pk_bf16_f32 v2, v2, v3
	v_cvt_pk_bf16_f32 v3, v4, v5
	v_add_co_u32_e32 v4, vcc, s0, v60
	v_cvt_pk_bf16_f32 v18, v18, v19
	v_cvt_pk_bf16_f32 v19, v20, v21
	v_addc_co_u32_e32 v5, vcc, 0, v61, vcc
	s_mov_b64 s[98:99], exec
	s_mov_b32 exec_lo, s32
	s_mov_b32 exec_hi, 0
	v_mov_b32_e32 v253, 1
	global_atomic_add v252, v1, v253, s[30:31] sc0
	s_mov_b64 exec, s[98:99]
	v_mov_b32_e32 v240, v18
	v_mov_b32_e32 v241, v19
	v_mov_b32_e32 v244, v2
	v_mov_b32_e32 v245, v3
	v_pk_mul_f32 v[2:3], v[22:23], v[0:1] op_sel_hi:[1,0]
	v_pk_mul_f32 v[4:5], v[24:25], v[0:1] op_sel_hi:[1,0]
	v_cvt_pk_bf16_f32 v2, v2, v3
	v_cvt_pk_bf16_f32 v3, v4, v5
	v_pk_mul_f32 v[4:5], v[6:7], v[0:1] op_sel_hi:[1,0]
	v_pk_mul_f32 v[6:7], v[8:9], v[0:1] op_sel_hi:[1,0]
	v_cvt_pk_bf16_f32 v4, v4, v5
	v_cvt_pk_bf16_f32 v5, v6, v7
	v_mov_b32_e32 v242, v2
	v_mov_b32_e32 v243, v3
	v_mbcnt_lo_u32_b32 v222, -1, 0
	v_mbcnt_hi_u32_b32 v222, -1, v222
	v_lshrrev_b32_e32 v222, 5, v222
	v_lshlrev_b32_e32 v222, 3, v222
	v_mov_b32_e32 v223, 0
	v_permlane32_swap_b32_e32 v240, v242
	v_permlane32_swap_b32_e32 v241, v243
	v_lshl_add_u64 v[222:223], v[62:63], 0, v[222:223]
	global_store_dwordx4 v[222:223], v[240:243], off sc1
	v_mov_b32_e32 v246, v4
	v_mov_b32_e32 v247, v5
	v_mbcnt_lo_u32_b32 v222, -1, 0
	v_mbcnt_hi_u32_b32 v222, -1, v222
	v_lshrrev_b32_e32 v222, 5, v222
	v_lshlrev_b32_e32 v222, 3, v222
	v_mov_b32_e32 v223, 0
	v_permlane32_swap_b32_e32 v244, v246
	v_permlane32_swap_b32_e32 v245, v247
	v_lshl_add_u64 v[222:223], v[62:63], 0, v[222:223]
	global_store_dwordx4 v[222:223], v[244:247], off offset:64 sc1
	v_pk_mul_f32 v[2:3], v[26:27], v[0:1] op_sel_hi:[1,0]
	v_pk_mul_f32 v[4:5], v[28:29], v[0:1] op_sel_hi:[1,0]
	v_cvt_pk_bf16_f32 v2, v2, v3
	v_cvt_pk_bf16_f32 v3, v4, v5
	v_pk_mul_f32 v[4:5], v[10:11], v[0:1] op_sel_hi:[1,0]
	v_pk_mul_f32 v[6:7], v[12:13], v[0:1] op_sel_hi:[1,0]
	v_cvt_pk_bf16_f32 v4, v4, v5
	v_cvt_pk_bf16_f32 v5, v6, v7
	v_mov_b32_e32 v240, v2
	v_mov_b32_e32 v241, v3
	v_mov_b32_e32 v244, v4
	v_mov_b32_e32 v245, v5
	v_pk_mul_f32 v[2:3], v[30:31], v[0:1] op_sel_hi:[1,0]
	v_pk_mul_f32 v[4:5], v[32:33], v[0:1] op_sel_hi:[1,0]
	v_cvt_pk_bf16_f32 v2, v2, v3
	v_cvt_pk_bf16_f32 v3, v4, v5
	v_pk_mul_f32 v[4:5], v[14:15], v[0:1] op_sel_hi:[1,0]
	v_pk_mul_f32 v[6:7], v[16:17], v[0:1] op_sel_hi:[1,0]
	v_cvt_pk_bf16_f32 v4, v4, v5
	v_cvt_pk_bf16_f32 v5, v6, v7
	v_mov_b32_e32 v242, v2
	v_mov_b32_e32 v243, v3
	v_mbcnt_lo_u32_b32 v222, -1, 0
	v_mbcnt_hi_u32_b32 v222, -1, v222
	v_lshrrev_b32_e32 v222, 5, v222
	v_lshlrev_b32_e32 v222, 3, v222
	v_mov_b32_e32 v223, 0
	v_permlane32_swap_b32_e32 v240, v242
	v_permlane32_swap_b32_e32 v241, v243
	v_lshl_add_u64 v[222:223], v[62:63], 0, v[222:223]
	global_store_dwordx4 v[222:223], v[240:243], off offset:32 sc1
	v_mov_b32_e32 v246, v4
	v_mov_b32_e32 v247, v5
	v_mbcnt_lo_u32_b32 v222, -1, 0
	v_mbcnt_hi_u32_b32 v222, -1, v222
	v_lshrrev_b32_e32 v222, 5, v222
	v_lshlrev_b32_e32 v222, 3, v222
	v_mov_b32_e32 v223, 0
	v_permlane32_swap_b32_e32 v244, v246
	v_permlane32_swap_b32_e32 v245, v247
	v_lshl_add_u64 v[222:223], v[62:63], 0, v[222:223]
	global_store_dwordx4 v[222:223], v[244:247], off offset:96 sc1
	s_barrier

.LBB0_1796:
	s_mov_b64 s[98:99], exec
	s_mov_b32 exec_lo, s32
	s_mov_b32 exec_hi, 0
	v_mov_b32_e32 v253, 1
	global_atomic_add v252, v1, v253, s[30:31] sc0
	s_mov_b64 exec, s[98:99]
	v_mov_b32_e32 v0, v1
	s_waitcnt vmcnt(0)
	s_barrier
	s_getreg_b32 s2, hwreg(HW_REG_HW_ID, 0, 6)
	s_lshl_b32 s2, s2, 2
	s_and_b32 s2, s2, 0xfc
	v_add_u32_e32 v2, s2, v0
	v_add_u32_e32 v2, 0x24800, v2
	ds_read_b32 v2, v2
	v_mbcnt_lo_u32_b32 v0, -1, v0
	v_mbcnt_hi_u32_b32 v0, -1, v0
	s_waitcnt lgkmcnt(0)
	v_readfirstlane_b32 s2, v2
	s_lshl_b32 s2, s2, 6
	s_sub_i32 s2, 0, s2
	v_cmp_eq_u32_e32 vcc, s2, v0
	s_and_saveexec_b64 s[2:3], vcc
	s_xor_b64 s[2:3], exec, s[2:3]
	s_cbranch_execz .LBB0_1515
	s_mov_b64 s[4:5], exec
	buffer_wbl2 sc1
	s_waitcnt vmcnt(0)
	s_waitcnt vmcnt(0)
	v_mbcnt_lo_u32_b32 v0, s4, 0
	v_mbcnt_hi_u32_b32 v0, s5, v0
	v_cmp_eq_u32_e32 vcc, 0, v0
	s_and_saveexec_b64 s[6:7], vcc
	s_xor_b64 s[6:7], exec, s[6:7]
	s_cbranch_execz .LBB0_1514
	s_and_b64 s[0:1], s[0:1], exec
	s_cselect_b32 s1, s93, s37
	s_cselect_b32 s0, s92, s36
	s_bcnt1_i32_b64 s4, s[4:5]
	v_mov_b32_e32 v0, s4
	global_atomic_add v1, v0, s[0:1]
	s_branch .LBB0_1514
